# on top of the rebalanced K-loops: stick-breaking tile loop waits only for the K pieces (vmcnt 8) before the QK reads, V pieces waited right before the transposed V reads
# speedup vs baseline: 1.0005x; 1.0005x over previous
.LBB0_294:
	s_sub_i32 s86, s2, 56
	s_lshl_b64 s[94:95], s[86:87], 11
	v_lshl_add_u64 v[32:33], v[116:117], 0, s[94:95]
	s_mov_b32 s3, m0
	s_mov_b32 m0, s82
	s_nop 0
	global_load_lds_dwordx4 v[32:33], off
	s_mov_b32 m0, s3
	s_sub_i32 s86, s2, 48
	s_lshl_b64 s[96:97], s[86:87], 11
	s_add_i32 s3, s82, 0x400
	s_sub_i32 s86, s2, 40
	v_lshl_add_u64 v[32:33], v[116:117], 0, s[96:97]
	s_mov_b32 s81, m0
	s_mov_b32 m0, s3
	s_nop 0
	global_load_lds_dwordx4 v[32:33], off
	s_mov_b32 m0, s81
	s_lshl_b64 s[96:97], s[86:87], 11
	s_add_i32 s3, s82, 0x800
	s_sub_i32 s86, s2, 32
	v_lshl_add_u64 v[32:33], v[116:117], 0, s[96:97]
	s_mov_b32 s81, m0
	s_mov_b32 m0, s3
	s_nop 0
	global_load_lds_dwordx4 v[32:33], off
	s_mov_b32 m0, s81
	s_lshl_b64 vcc, s[86:87], 11
	s_add_i32 s3, s82, 0xc00
	s_sub_i32 s86, s2, 24
	v_lshl_add_u64 v[32:33], v[116:117], 0, vcc
	s_mov_b32 s81, m0
	s_mov_b32 m0, s3
	s_nop 0
	global_load_lds_dwordx4 v[32:33], off
	s_mov_b32 m0, s81
	s_lshl_b64 vcc, s[86:87], 11
	s_add_i32 s3, s82, 0x1000
	s_add_i32 s86, s2, -16
	v_lshl_add_u64 v[32:33], v[116:117], 0, vcc
	s_mov_b32 s81, m0
	s_mov_b32 m0, s3
	s_nop 0
	global_load_lds_dwordx4 v[32:33], off
	s_mov_b32 m0, s81
	s_lshl_b64 s[88:89], s[86:87], 11
	s_add_i32 s3, s82, 0x1400
	s_add_i32 s86, s2, -8
	v_lshl_add_u64 v[32:33], v[116:117], 0, s[88:89]
	s_mov_b32 s81, m0
	s_mov_b32 m0, s3
	s_nop 0
	global_load_lds_dwordx4 v[32:33], off
	s_mov_b32 m0, s81
	s_lshl_b64 s[88:89], s[86:87], 11
	s_add_i32 s3, s82, 0x1800
	v_lshl_add_u64 v[32:33], v[116:117], 0, s[88:89]
	s_mov_b32 s81, m0
	s_mov_b32 m0, s3
	s_nop 0
	global_load_lds_dwordx4 v[32:33], off
	s_mov_b32 m0, s81
	s_mov_b32 s3, s87
	s_lshl_b64 s[90:91], s[2:3], 11
	v_lshl_add_u64 v[32:33], v[116:117], 0, s[90:91]
	s_add_i32 s3, s82, 0x1c00
	s_mov_b32 s81, m0
	s_mov_b32 m0, s3
	s_nop 0
	global_load_lds_dwordx4 v[32:33], off
	s_mov_b32 m0, s81
	v_lshl_add_u64 v[32:33], v[118:119], 0, s[94:95]
	s_mov_b32 s3, m0
	s_mov_b32 m0, s83
	s_nop 0
	global_load_lds_dwordx4 v[32:33], off
	s_mov_b32 m0, s3
	v_lshl_add_u64 v[34:35], v[118:119], 0, s[96:97]
	s_add_i32 s3, s82, 0x2400
	s_mov_b32 s81, m0
	s_mov_b32 m0, s3
	s_nop 0
	global_load_lds_dwordx4 v[34:35], off
	s_mov_b32 m0, s81
	v_lshl_add_u64 v[36:37], v[118:119], 0, vcc
	s_add_i32 s3, s82, 0x2800
	s_mov_b32 s81, m0
	s_mov_b32 m0, s3
	s_nop 0
	global_load_lds_dwordx4 v[36:37], off
	s_mov_b32 m0, s81
	v_lshl_add_u64 v[38:39], v[118:119], 0, s[88:89]
	s_add_i32 s3, s82, 0x2c00
	s_mov_b32 s81, m0
	s_mov_b32 m0, s3
	s_nop 0
	global_load_lds_dwordx4 v[38:39], off
	s_mov_b32 m0, s81
	v_lshl_add_u64 v[32:33], v[32:33], 0, 64
	s_add_i32 s3, s82, 0x3000
	s_mov_b32 s81, m0
	s_mov_b32 m0, s3
	s_nop 0
	global_load_lds_dwordx4 v[32:33], off
	s_mov_b32 m0, s81
	v_lshl_add_u64 v[32:33], v[34:35], 0, 64
	s_add_i32 s3, s82, 0x3400
	s_mov_b32 s81, m0
	s_mov_b32 m0, s3
	s_nop 0
	global_load_lds_dwordx4 v[32:33], off
	s_mov_b32 m0, s81
	v_lshl_add_u64 v[32:33], v[36:37], 0, 64
	s_add_i32 s3, s82, 0x3800
	s_mov_b32 s81, m0
	s_mov_b32 m0, s3
	s_nop 0
	global_load_lds_dwordx4 v[32:33], off
	s_mov_b32 m0, s81
	v_lshl_add_u64 v[32:33], v[38:39], 0, 64
	s_add_i32 s3, s82, 0x3c00
	s_mov_b32 s81, m0
	s_mov_b32 m0, s3
	s_nop 0
	global_load_lds_dwordx4 v[32:33], off
	s_mov_b32 m0, s81
	s_waitcnt vmcnt(8)
	ds_read_b128 v[32:35], v115
	ds_read_b128 v[48:51], v115 offset:4096
	ds_read_b128 v[80:83], v166
	ds_read_b128 v[84:87], v166 offset:4096
	ds_read_b128 v[88:91], v167
	ds_read_b128 v[92:95], v167 offset:4096
	ds_read_b128 v[96:99], v168
	ds_read_b128 v[100:103], v168 offset:4096
	s_waitcnt vmcnt(8) lgkmcnt(0)
	v_mfma_f32_32x32x16_bf16 v[32:47], v[32:35], v[76:79], 0
	v_mfma_f32_32x32x16_bf16 v[48:63], v[48:51], v[76:79], 0
	v_mfma_f32_32x32x16_bf16 v[32:47], v[80:83], v[72:75], v[32:47]
	v_mfma_f32_32x32x16_bf16 v[48:63], v[84:87], v[72:75], v[48:63]
	v_mfma_f32_32x32x16_bf16 v[32:47], v[88:91], v[68:71], v[32:47]
	v_mfma_f32_32x32x16_bf16 v[48:63], v[92:95], v[68:71], v[48:63]
	v_mfma_f32_32x32x16_bf16 v[32:47], v[96:99], v[64:67], v[32:47]
	v_mfma_f32_32x32x16_bf16 v[48:63], v[100:103], v[64:67], v[48:63]
	s_waitcnt vmcnt(0)
	ds_read_b64_tr_b16 v[88:89], v169 offset:8192
	ds_read_b64_tr_b16 v[90:91], v169 offset:8704
	ds_read_b64_tr_b16 v[84:85], v169 offset:12288
	ds_read_b64_tr_b16 v[86:87], v169 offset:12800
	ds_read_b64_tr_b16 v[92:93], v169 offset:9216
	ds_read_b64_tr_b16 v[94:95], v169 offset:9728
	ds_read_b64_tr_b16 v[108:109], v169 offset:13312
	ds_read_b64_tr_b16 v[110:111], v169 offset:13824
	ds_read_b64_tr_b16 v[104:105], v169 offset:10240
	ds_read_b64_tr_b16 v[106:107], v169 offset:10752
	ds_read_b64_tr_b16 v[96:97], v169 offset:14336
	ds_read_b64_tr_b16 v[98:99], v169 offset:14848
	ds_read_b64_tr_b16 v[100:101], v169 offset:11264
	ds_read_b64_tr_b16 v[102:103], v169 offset:11776
	ds_read_b64_tr_b16 v[80:81], v169 offset:15360
	ds_read_b64_tr_b16 v[82:83], v169 offset:15872
	s_cmp_lg_u32 s80, 0
	s_cbranch_scc0 .LBB0_297
	v_exp_f32_e64 v120, -|v51|
	v_exp_f32_e64 v112, -|v48|
	v_and_b32_e32 v125, 0x7fffffff, v55
	v_and_b32_e32 v124, 0x7fffffff, v54
	v_add_f32_e32 v120, 1.0, v120
	v_add_f32_e32 v112, 1.0, v112
	v_log_f32_e32 v122, v120
	v_log_f32_e32 v146, v112
	v_add_f32_e64 v120, v51, |v51|
	v_add_f32_e64 v112, v48, |v48|
	v_fmac_f32_e32 v122, 0.5, v120
	v_exp_f32_e64 v120, -|v55|
	v_fmac_f32_e32 v146, 0.5, v112
	v_exp_f32_e64 v112, -|v54|
	v_pk_add_f32 v[124:125], v[54:55], v[124:125]
	v_add_f32_e32 v120, 1.0, v120
	v_log_f32_e32 v127, v120
	v_add_f32_e32 v112, 1.0, v112
	v_exp_f32_e64 v120, -|v59|
	v_log_f32_e32 v126, v112
	v_exp_f32_e64 v112, -|v56|
	v_add_f32_e64 v123, v56, |v56|
	v_add_f32_e32 v120, 1.0, v120
	v_pk_fma_f32 v[126:127], v[124:125], 0.5, v[126:127] op_sel_hi:[1,0,1]
	v_log_f32_e32 v124, v120
	v_exp_f32_e64 v120, -|v62|
	v_exp_f32_e64 v125, -|v63|
	v_add_f32_e32 v112, 1.0, v112
	v_log_f32_e32 v112, v112
	v_add_f32_e32 v120, 1.0, v120
	v_log_f32_e32 v128, v120
	v_add_f32_e32 v120, 1.0, v125
	v_log_f32_e32 v129, v120
	v_exp_f32_e64 v120, -|v57|
	v_fmac_f32_e32 v112, 0.5, v123
	v_add_f32_e64 v123, v59, |v59|
	v_fmac_f32_e32 v124, 0.5, v123
	v_add_f32_e32 v120, 1.0, v120
	v_log_f32_e32 v138, v120
	v_exp_f32_e64 v120, -|v58|
	v_exp_f32_e64 v123, -|v60|
	v_exp_f32_e64 v125, -|v61|
	v_and_b32_e32 v131, 0x7fffffff, v63
	v_add_f32_e32 v120, 1.0, v120
	v_log_f32_e32 v144, v120
	v_add_f32_e32 v120, 1.0, v123
	v_log_f32_e32 v139, v120
	v_add_f32_e32 v120, 1.0, v125
	v_and_b32_e32 v130, 0x7fffffff, v62
	v_log_f32_e32 v145, v120
	v_pk_add_f32 v[130:131], v[62:63], v[130:131]
	v_and_b32_e32 v135, 0x7fffffff, v60
	v_mov_b32_e32 v136, v57
	v_mov_b32_e32 v137, v60
	v_and_b32_e32 v134, 0x7fffffff, v57
	v_pk_fma_f32 v[128:129], v[130:131], 0.5, v[128:129] op_sel_hi:[1,0,1]
	v_and_b32_e32 v141, 0x7fffffff, v61
	v_mov_b32_e32 v142, v58
	v_mov_b32_e32 v143, v61
	v_and_b32_e32 v140, 0x7fffffff, v58
	v_pk_add_f32 v[134:135], v[136:137], v[134:135]
	v_pk_add_f32 v[130:131], v[128:129], v[128:129] op_sel:[0,1] op_sel_hi:[1,0]
	v_pk_fma_f32 v[136:137], v[134:135], 0.5, v[138:139] op_sel_hi:[1,0,1]
	v_pk_add_f32 v[134:135], v[142:143], v[140:141]
	v_mov_b32_e32 v125, v130
	v_pk_fma_f32 v[134:135], v[134:135], 0.5, v[144:145] op_sel_hi:[1,0,1]
	v_exp_f32_e64 v120, -|v52|
	v_pk_add_f32 v[134:135], v[134:135], v[124:125]
	v_exp_f32_e64 v123, -|v53|
	v_pk_add_f32 v[136:137], v[136:137], v[134:135]
	v_and_b32_e32 v143, 0x7fffffff, v52
	v_pk_add_f32 v[138:139], v[112:113], v[136:137]
	v_exp_f32_e64 v112, -|v49|
	v_mov_b32_e32 v144, v49
	v_mov_b32_e32 v145, v52
	v_and_b32_e32 v142, 0x7fffffff, v49
	v_add_f32_e32 v112, 1.0, v112
	v_log_f32_e32 v148, v112
	v_exp_f32_e64 v112, -|v50|
	v_and_b32_e32 v151, 0x7fffffff, v53
	v_mov_b32_e32 v152, v50
	v_mov_b32_e32 v153, v53
	v_add_f32_e32 v112, 1.0, v112
	v_log_f32_e32 v154, v112
	v_add_f32_e32 v112, 1.0, v120
	v_log_f32_e32 v149, v112
	v_add_f32_e32 v112, 1.0, v123
	v_log_f32_e32 v155, v112
	v_and_b32_e32 v150, 0x7fffffff, v50
	v_pk_add_f32 v[142:143], v[144:145], v[142:143]
	v_pk_add_f32 v[132:133], v[126:127], v[126:127] op_sel:[0,1] op_sel_hi:[1,0]
	v_pk_fma_f32 v[144:145], v[142:143], 0.5, v[148:149] op_sel_hi:[1,0,1]
	v_pk_add_f32 v[142:143], v[152:153], v[150:151]
	v_mov_b32_e32 v123, v132
	v_pk_fma_f32 v[142:143], v[142:143], 0.5, v[154:155] op_sel_hi:[1,0,1]
	v_pk_add_f32 v[140:141], v[138:139], v[138:139] op_sel:[0,1] op_sel_hi:[1,0]
	v_pk_add_f32 v[142:143], v[142:143], v[122:123]
	v_mov_b32_e32 v147, v140
	v_pk_add_f32 v[144:145], v[144:145], v[142:143]
	v_mov_b32_e32 v125, v140
	v_pk_add_f32 v[146:147], v[146:147], v[144:145]
	v_mov_b32_e32 v126, v140
	v_add_f32_e32 v112, v146, v147
	v_mov_b32_e32 v120, v112
	v_mov_b32_e32 v123, v147
	s_nop 1
	v_permlane32_swap_b32_e32 v120, v123
	v_cndmask_b32_e64 v123, v120, v123, s[74:75]
	v_add_f32_e32 v112, v112, v123
	v_mov_b32_e32 v120, v112
	v_mov_b32_e32 v133, v112
	s_nop 1
	v_permlane32_swap_b32_e32 v120, v133
	v_cndmask_b32_e64 v120, v120, v133, s[74:75]
	v_cndmask_b32_e64 v112, v120, v112, s[74:75]
	v_add_f32_e32 v120, v121, v112
	v_mov_b32_e32 v131, v147
	v_mov_b32_e32 v141, v139
	v_mov_b32_e32 v128, v139
	v_mov_b32_e32 v170, 0
	v_cmp_lt_f32_e32 vcc, s84, v120
	v_permlane32_swap_b32_e32 v131, v125
	v_permlane32_swap_b32_e32 v126, v141
	s_cmp_eq_u64 vcc, exec
	v_permlane32_swap_b32_e32 v128, v170
	s_cbranch_scc1 .LBB0_298
	v_exp_f32_e64 v112, -|v32|
	v_add_f32_e64 v133, v40, |v40|
	v_and_b32_e32 v153, 0x7fffffff, v39
	v_and_b32_e32 v152, 0x7fffffff, v38
	v_add_f32_e32 v112, 1.0, v112
	v_log_f32_e32 v150, v112
	v_add_f32_e64 v112, v32, |v32|
	v_pk_add_f32 v[152:153], v[38:39], v[152:153]
	v_and_b32_e32 v157, 0x7fffffff, v47
	v_fmac_f32_e32 v150, 0.5, v112
	v_exp_f32_e64 v112, -|v35|
	v_and_b32_e32 v156, 0x7fffffff, v46
	v_pk_add_f32 v[156:157], v[46:47], v[156:157]
	v_and_b32_e32 v173, 0x7fffffff, v44
	v_add_f32_e32 v112, 1.0, v112
	v_log_f32_e32 v148, v112
	v_add_f32_e64 v112, v35, |v35|
	v_mov_b32_e32 v174, v41
	v_mov_b32_e32 v175, v44
	v_fmac_f32_e32 v148, 0.5, v112
	v_exp_f32_e64 v112, -|v38|
	v_and_b32_e32 v172, 0x7fffffff, v41
	v_and_b32_e32 v179, 0x7fffffff, v45
	v_mov_b32_e32 v180, v42
	v_add_f32_e32 v112, 1.0, v112
	v_log_f32_e32 v154, v112
	v_exp_f32_e64 v112, -|v39|
	v_mov_b32_e32 v181, v45
	v_and_b32_e32 v178, 0x7fffffff, v42
	v_pk_add_f32 v[172:173], v[174:175], v[172:173]
	v_add_f32_e32 v112, 1.0, v112
	v_log_f32_e32 v155, v112
	v_exp_f32_e64 v112, -|v40|
	v_pk_add_f32 v[174:175], v[180:181], v[178:179]
	v_and_b32_e32 v181, 0x7fffffff, v36
	v_pk_fma_f32 v[152:153], v[152:153], 0.5, v[154:155] op_sel_hi:[1,0,1]
	v_add_f32_e32 v112, 1.0, v112
	v_log_f32_e32 v112, v112
	v_and_b32_e32 v180, 0x7fffffff, v33
	v_and_b32_e32 v189, 0x7fffffff, v37
	v_mov_b32_e32 v192, v34
	v_fmac_f32_e32 v112, 0.5, v133
	v_exp_f32_e64 v133, -|v43|
	v_mov_b32_e32 v193, v37
	v_and_b32_e32 v188, 0x7fffffff, v34
	v_pk_add_f32 v[160:161], v[152:153], v[152:153] op_sel:[0,1] op_sel_hi:[1,0]
	v_add_f32_e32 v133, 1.0, v133
	v_log_f32_e32 v154, v133
	v_add_f32_e64 v133, v43, |v43|
	v_mov_b32_e32 v149, v160
	s_mov_b64 s[94:95], 0
	v_fmac_f32_e32 v154, 0.5, v133
	v_exp_f32_e64 v133, -|v46|
	s_nop 0
	v_add_f32_e32 v133, 1.0, v133
	v_log_f32_e32 v158, v133
	v_exp_f32_e64 v133, -|v47|
	s_nop 0
	v_add_f32_e32 v133, 1.0, v133
	v_log_f32_e32 v159, v133
	v_exp_f32_e64 v133, -|v41|
	v_pk_fma_f32 v[156:157], v[156:157], 0.5, v[158:159] op_sel_hi:[1,0,1]
	v_add_f32_e32 v133, 1.0, v133
	v_log_f32_e32 v176, v133
	v_exp_f32_e64 v133, -|v42|
	v_pk_add_f32 v[158:159], v[156:157], v[156:157] op_sel:[0,1] op_sel_hi:[1,0]
	v_add_f32_e32 v133, 1.0, v133
	v_log_f32_e32 v182, v133
	v_exp_f32_e64 v133, -|v44|
	v_mov_b32_e32 v155, v158
	v_add_f32_e32 v133, 1.0, v133
	v_log_f32_e32 v177, v133
	v_exp_f32_e64 v133, -|v45|
	v_pk_fma_f32 v[172:173], v[172:173], 0.5, v[176:177] op_sel_hi:[1,0,1]
	v_add_f32_e32 v133, 1.0, v133
	v_log_f32_e32 v183, v133
	s_nop 0
	v_pk_fma_f32 v[174:175], v[174:175], 0.5, v[182:183] op_sel_hi:[1,0,1]
	s_nop 0
	v_pk_add_f32 v[174:175], v[174:175], v[154:155]
	v_mov_b32_e32 v182, v33
	v_pk_add_f32 v[172:173], v[172:173], v[174:175]
	v_mov_b32_e32 v183, v36
	v_pk_add_f32 v[176:177], v[112:113], v[172:173]
	v_exp_f32_e64 v112, -|v33|
	v_pk_add_f32 v[180:181], v[182:183], v[180:181]
	v_pk_add_f32 v[182:183], v[192:193], v[188:189]
	v_pk_add_f32 v[178:179], v[176:177], v[176:177] op_sel:[0,1] op_sel_hi:[1,0]
	v_add_f32_e32 v112, 1.0, v112
	v_log_f32_e32 v186, v112
	v_exp_f32_e64 v112, -|v34|
	v_mov_b32_e32 v151, v178
	v_add_f32_e32 v152, v177, v120
	v_add_f32_e32 v155, 0, v120
	v_add_f32_e32 v112, 1.0, v112
	v_log_f32_e32 v194, v112
	v_exp_f32_e64 v112, -|v36|
	s_nop 0
	v_add_f32_e32 v112, 1.0, v112
	v_log_f32_e32 v187, v112
	v_exp_f32_e64 v112, -|v37|
	v_pk_fma_f32 v[180:181], v[180:181], 0.5, v[186:187] op_sel_hi:[1,0,1]
	v_add_f32_e32 v112, 1.0, v112
	v_log_f32_e32 v195, v112
	s_nop 0
	v_pk_fma_f32 v[182:183], v[182:183], 0.5, v[194:195] op_sel_hi:[1,0,1]
	s_nop 0
	v_pk_add_f32 v[186:187], v[182:183], v[148:149]
	s_nop 0
	v_pk_add_f32 v[188:189], v[180:181], v[186:187]
	s_nop 0
	v_pk_add_f32 v[150:151], v[150:151], v[188:189]
	s_nop 0
	v_add_f32_e32 v112, v150, v151
	v_mov_b32_e32 v133, v112
	v_mov_b32_e32 v149, v151
	s_nop 1
	v_permlane32_swap_b32_e32 v133, v149
	v_cndmask_b32_e64 v133, v133, v149, s[74:75]
	v_add_f32_e32 v149, v151, v120
	v_add_f32_e32 v149, v149, v133
	v_add_f32_e32 v112, v112, v133
	v_mov_b32_e32 v133, v178
	s_nop 1
	v_permlane32_swap_b32_e32 v151, v133
	v_cndmask_b32_e64 v133, v151, v133, s[74:75]
	v_add_f32_e32 v151, v178, v120
	v_add_f32_e32 v151, v151, v133
	v_mov_b32_e32 v133, v177
	s_nop 1
	v_permlane32_swap_b32_e32 v178, v133
	v_cndmask_b32_e64 v133, v178, v133, s[74:75]
	v_add_f32_e32 v152, v152, v133
	v_mov_b32_e32 v133, v113
	s_nop 1
	v_permlane32_swap_b32_e32 v177, v133
	v_cndmask_b32_e64 v133, v177, v133, s[74:75]
	v_add_f32_e32 v155, v155, v133
	v_mov_b32_e32 v133, v112
	v_mov_b32_e32 v156, v112
	s_nop 1
	v_permlane32_swap_b32_e32 v133, v156
	v_cndmask_b32_e64 v133, v133, v156, s[74:75]
	v_cndmask_b32_e64 v112, v133, v112, s[74:75]
	v_add_f32_e32 v120, v120, v112
	v_add_f32_e32 v112, v150, v149
	v_sub_f32_e32 v112, v32, v112
	v_exp_f32_e32 v133, v112
	v_add_f32_e32 v112, v188, v149
	v_sub_f32_e32 v112, v33, v112
	v_exp_f32_e32 v179, v112
	v_add_f32_e32 v112, v186, v149
	v_sub_f32_e32 v112, v34, v112
	v_exp_f32_e32 v181, v112
	v_add_f32_e32 v112, v148, v149
	v_add_f32_e32 v148, v172, v152
	v_sub_f32_e32 v148, v41, v148
	v_exp_f32_e32 v177, v148
	v_add_f32_e32 v148, v174, v152
	v_sub_f32_e32 v112, v35, v112
	v_sub_f32_e32 v148, v42, v148
	v_exp_f32_e32 v183, v112
	v_add_f32_e32 v112, v189, v151
	v_exp_f32_e32 v178, v148
	v_add_f32_e32 v148, v154, v152
	v_sub_f32_e32 v112, v36, v112
	v_sub_f32_e32 v148, v43, v148
	v_exp_f32_e32 v186, v112
	v_add_f32_e32 v112, v187, v151
	v_exp_f32_e32 v180, v148
	v_add_f32_e32 v148, v173, v155
	v_sub_f32_e32 v112, v37, v112
	v_sub_f32_e32 v148, v44, v148
	v_exp_f32_e32 v188, v112
	v_add_f32_e32 v112, v160, v151
	v_exp_f32_e32 v182, v148
	v_add_f32_e32 v148, v175, v155
	v_sub_f32_e32 v112, v38, v112
	v_sub_f32_e32 v148, v45, v148
	v_exp_f32_e32 v191, v112
	v_add_f32_e32 v112, v153, v151
	v_exp_f32_e32 v185, v148
	v_add_f32_e32 v148, v158, v155
	v_sub_f32_e32 v112, v39, v112
	v_sub_f32_e32 v148, v46, v148
	v_exp_f32_e32 v192, v112
	v_add_f32_e32 v112, v176, v152
	v_exp_f32_e32 v187, v148
	v_add_f32_e32 v148, v157, v155
	v_sub_f32_e32 v112, v40, v112
	v_sub_f32_e32 v148, v47, v148
	v_exp_f32_e32 v112, v112
	v_exp_f32_e32 v189, v148
	s_branch .LBB0_299
